# PRE prologue: constant-table LDS writes and their workgroup barrier moved behind the first item's row loads so both fetches overlap
# baseline (speedup 1.0000x reference)
.Lctb_done:
	s_load_dwordx2 s[38:39], s[94:95], s28
	v_add_lshl_u32 v1, s1, v180, 2
	v_add_lshl_u32 v4, s29, v180, 2
	s_lshl_b32 s3, s66, 8
	s_add_u32 s3, s3, 0x24700
	v_lshl_add_u32 v23, v180, 2, s3
	s_cmp_lg_u32 s66, 0
	s_cbranch_scc1 .Lct_two
	s_mov_b32 s50, 16
	s_lshl_b32 s40, s50, 3
	s_add_u32 s40, s40, 0x60
	s_lshl_b32 s41, s26, 9
	s_add_u32 s41, s41, s27
	s_cmp_lt_u32 s50, 3
	s_cbranch_scc1 .Lctc_done
	s_sub_u32 s3, s50, 3
	s_cmp_lt_u32 s3, 4
	s_cbranch_scc0 .Lctc_7
	s_lshr_b32 s40, s3, 1
	s_lshl_b32 s40, s40, 4
	s_add_u32 s40, s40, 0x38
	s_and_b32 s3, s3, 1
	s_lshl_b32 s41, s26, 1
	s_add_u32 s41, s41, s3
	s_lshl_b32 s41, s41, 9
	s_add_u32 s41, s41, s27
	s_branch .Lctc_done

.Lctc_done:
	s_load_dwordx2 s[48:49], s[94:95], s40
	v_add_lshl_u32 v9, s41, v180, 2
	s_waitcnt lgkmcnt(0)
	global_load_dword v20, v1, s[36:37]
	global_load_dword v21, v4, s[38:39]
	global_load_dword v22, v9, s[48:49]
	s_branch .Lct_end
.Lct_two:
	s_waitcnt lgkmcnt(0)
	global_load_dword v20, v1, s[36:37]
	global_load_dword v21, v4, s[38:39]
.Lct_end:
.LBB0_62:
	s_or_b64 exec, exec, s[24:25]
	v_mov_b32_e32 v3, v180
	s_waitcnt lgkmcnt(0)
	v_readlane_b32 s0, v252, 18
	v_add_u32_e32 v1, s42, v3
	v_ashrrev_i32_e32 v1, 3, v1
	v_add_u32_e32 v1, s0, v1
	v_readlane_b32 s0, v252, 19
	v_lshlrev_b32_e32 v3, 3, v3
	s_waitcnt lgkmcnt(0)
	s_mov_b64 s[98:99], s[30:31]
	s_add_u32 s24, s30, 0x7c00000
	v_add_u32_e32 v2, s0, v1
	v_and_b32_e32 v8, 56, v3
	v_ashrrev_i32_e32 v3, 31, v2
	s_addc_u32 s25, s31, 0
	v_lshlrev_b64 v[4:5], 9, v[2:3]
	v_writelane_b32 v255, s24, 3
	v_lshlrev_b32_e32 v6, 1, v8
	v_mov_b32_e32 v7, v0
	v_lshl_add_u64 v[2:3], s[24:25], 0, v[4:5]
	v_lshl_add_u64 v[6:7], v[2:3], 0, v[6:7]
	global_load_dwordx4 v[100:103], v[6:7], off
	v_mov_b32_e32 v106, v0
	v_mov_b32_e32 v107, v0
	v_mov_b32_e32 v104, v0
	v_mov_b32_e32 v105, v0
	v_mov_b64_e32 v[110:111], v[106:107]
	v_writelane_b32 v255, s25, 4
	v_cmp_lt_i32_e32 vcc, 0, v1
	v_mov_b64_e32 v[108:109], v[104:105]
	s_and_saveexec_b64 s[26:27], vcc
	s_cbranch_execz .LBB0_64
	global_load_dwordx4 v[108:111], v[6:7], off offset:-512

.LBB0_78:
	s_or_b64 exec, exec, s[38:39]
	v_readlane_b32 s0, v252, 22
	v_readlane_b32 s1, v252, 23
	s_andn2_b64 vcc, exec, s[0:1]
	s_cbranch_vccnz .LBB0_163
	s_ashr_i32 s0, s66, 2
	s_mul_i32 s1, s0, 0xfc00
	s_add_i32 s76, s1, 0
	s_lshl_b32 s1, s0, 8
	s_bfe_u32 s40, s66, 0x10001
	s_and_b32 s41, s66, 1
	s_add_i32 s26, s1, 0
	s_lshl_b32 s43, s40, 5
	s_lshl_b32 s91, s41, 5
	s_add_i32 s38, s76, 0x9000
	s_add_i32 s39, s76, 0xb400
	s_lshl_b32 s50, s0, 6
	s_add_i32 s87, s26, 0x24100
	s_add_u32 s48, s30, 0x6c00000
	s_addc_u32 s49, s31, 0
	s_ashr_i32 s1, s0, 31
	s_lshl_b64 s[24:25], s[0:1], 16
	s_add_u32 s3, s30, s24
	s_addc_u32 s24, s31, s25
	s_add_u32 s54, s3, 0x1b80000
	s_addc_u32 s55, s24, 0
	s_add_u32 s58, s3, 0x1ba0000
	s_addc_u32 s59, s24, 0
	s_lshl_b64 s[24:25], s[0:1], 19
	s_add_u32 s1, s30, s24
	s_addc_u32 s24, s31, s25
	s_lshl_b32 s3, s41, 8
	v_readlane_b32 s25, v252, 24
	s_or_b32 s77, s3, s25
	s_cmp_gt_u32 s66, 3
	s_cselect_b64 s[60:61], -1, 0
	s_lshl_b32 s25, s41, 7
	s_add_i32 s46, s26, s25
	s_add_i32 s47, s46, 0x24a00
	s_add_i32 s46, s46, 0x24c00
	s_lshl_b32 s28, s41, 6
	s_bitcmp1_b32 s66, 1
	s_cselect_b64 s[62:63], -1, 0
	s_lshl_b32 s0, s0, 9
	v_writelane_b32 v255, s96, 9
	s_add_i32 s25, s87, s25
	s_add_i32 s0, s0, 0
	v_writelane_b32 v255, s25, 10
	s_add_i32 s0, s0, 0x24300
	v_writelane_b32 v255, s0, 11
	s_add_i32 s0, s0, s3
	v_writelane_b32 v255, s0, 12
	s_cmp_eq_u32 s41, 0
	v_readlane_b32 s0, v253, 54
	s_cselect_b64 s[26:27], -1, 0
	s_add_u32 s0, s1, s0
	s_addc_u32 s1, s24, 0
	s_add_u32 s0, s0, 0x10400000
	s_addc_u32 s1, s1, 0
	s_cmp_lt_u32 s66, 4
	v_writelane_b32 v255, s0, 13
	s_cselect_b64 s[36:37], -1, 0
	s_waitcnt vmcnt(0)
	ds_write_b32 v23, v20
	ds_write_b32 v23, v21 offset:2048
	s_cmp_lg_u32 s66, 0
	s_cbranch_scc1 .Lct_put2
	ds_write_b32 v23, v22 offset:4096
.Lct_put2:
	s_waitcnt lgkmcnt(0)
	s_barrier
	v_writelane_b32 v255, s1, 14
	s_and_b64 s[0:1], s[36:37], exec
	v_readlane_b32 s0, v253, 61
	v_readlane_b32 s1, v253, 62
	s_cselect_b32 s29, s0, s1
	s_and_b32 s56, s66, 3
	s_cmp_eq_u32 s56, 0
	s_cselect_b64 s[72:73], -1, 0
	s_cmp_lg_u32 s56, 0
	s_cselect_b64 s[78:79], -1, 0
	s_cmp_eq_u32 s40, 0
	s_cselect_b64 s[24:25], -1, 0
	s_and_b64 s[0:1], s[24:25], exec
	s_cselect_b32 s1, s38, s39
	s_cmp_eq_u32 s40, s41
	s_cselect_b64 s[80:81], -1, 0
	s_lshl_b32 s0, s40, 6
	s_add_i32 s0, s76, s0
	s_and_b64 s[82:83], s[26:27], s[62:63]
	s_bitcmp1_b32 s66, 0
	s_cselect_b64 s[38:39], -1, 0
	s_and_b64 s[84:85], s[24:25], s[38:39]
	s_add_u32 s24, s30, 0xbc00000
	s_addc_u32 s25, s31, 0
	v_writelane_b32 v255, s24, 15
	s_brev_b32 s30, s56
	s_lshr_b32 s30, s30, 25
	v_writelane_b32 v255, s25, 16
	s_lshl_b32 s24, s40, 11
	s_lshl_b32 s25, s41, 10
	s_or_b32 s66, s24, s25
	v_readlane_b32 s24, v252, 25
	s_or_b32 s67, s77, 64
	s_or_b32 s94, s77, 0x80
	s_or_b32 s95, s77, 0xc0
	s_add_i32 s24, s50, s24
	s_or_b32 s25, s66, 0x200
	v_writelane_b32 v255, s30, 17
	s_xor_b64 s[96:97], s[26:27], -1
	v_readlane_b32 s26, v253, 51
	v_readlane_b32 s50, v252, 20
	s_branch .LBB0_81
